# P2 tail: exhausted attention queues of other XCDs are detected with one coherent load and skipped (no WBGEN wait, claim atomic, table load or second barrier)
# speedup vs baseline: 1.0070x; 1.0070x over previous
.LBB0_463:
	s_add_i32 s0, s55, s42
	s_and_b32 s10, s0, 7
	s_lshl_b32 s30, s10, 6
	s_and_saveexec_b64 s[0:1], s[2:3]
	s_cbranch_execz .LBB0_483
	s_cmp_eq_u32 s55, 0
	s_cbranch_scc1 .LBB0_480
	s_lshl_b32 s6, s30, 2
	v_mov_b32_e32 v2, s6
	global_load_dword v2, v2, s[16:17] sc1
	s_waitcnt vmcnt(0)
	v_cmp_lt_u32_e32 vcc, s45, v2
	s_cbranch_vccz .Lmy_p2_nonempty
	v_mov_b32_e32 v4, s46
	ds_write_b32 v4, v2
	s_branch .LBB0_483
.Lmy_p2_nonempty:
	v_mov_b32_e32 v2, s44
	ds_read_b32 v2, v2
	s_waitcnt lgkmcnt(0)
	v_cmp_eq_u32_e32 vcc, 0, v2
	s_cbranch_vccnz .LBB0_480
	s_lshl_b32 s6, s30, 2
	v_readlane_b32 s8, v255, 6
	v_readlane_b32 s9, v255, 7
	s_add_u32 s6, s8, s6
	s_addc_u32 s7, s9, 0
	global_load_dword v2, v203, s[6:7] offset:1536 sc1
	s_add_u32 s6, s6, 0x3600
	s_addc_u32 s7, s7, 0
	s_waitcnt vmcnt(0)
	v_cmp_ne_u32_e32 vcc, 0, v2
	s_cbranch_vccnz .LBB0_479
	s_mov_b32 s31, 1
	s_branch .LBB0_469

.LBB0_483:
	s_or_b64 exec, exec, s[0:1]
	s_waitcnt lgkmcnt(0)
	s_barrier
	v_mov_b32_e32 v2, s46
	ds_read_b32 v2, v2
	s_waitcnt lgkmcnt(0)
	v_readfirstlane_b32 s1, v2
	s_nop 1
	s_cmp_gt_u32 s1, 0xff
	s_cbranch_scc1 .LBB0_462
	s_and_saveexec_b64 s[0:1], s[4:5]
	s_cbranch_execz .LBB0_485
	v_lshlrev_b32_e32 v2, 2, v0
	v_lshl_or_b32 v2, s10, 9, v2
	global_load_dword v4, v2, s[22:23]
	v_add_u32_e32 v2, 0, v2
	v_add_u32_e32 v2, 0x22000, v2
	s_waitcnt vmcnt(0)
	ds_write_b32 v2, v4
